# MoBA block-score loop keeps 12 LDS reads in flight (same FMA order)
# speedup vs baseline: 1.0096x; 1.0096x over previous
; __device__ __forceinline__ float wave_sum(float v) { v += __shfl_xor(v, 1); v += __shfl_xor(v, 2); v += __shfl_xor(v, 4); v += __shfl_xor(v, 8); v += __shfl_xor(v, 16); v += __shfl_xor(v, 32); return v; }
; #define INP(k) ({ int k_ = (k); LAUNDER_S(k_); (const float*)(const GAS float*)P.in[k_]; })
; __global__ void __launch_bounds__(512, 2) hybrid_fwd(Params P) {
;     ...
;             if (gwave < 512) { const int kv = gwave >> 8, j = gwave & 255; const float* pp = INP(8) + (size_t)L * 2 * 2048 + kv * 2048; const float* ww = cw1 + (size_t)kv * 2048 * 256 + j; float a = 0.f;
; #pragma unroll 8
;                 for (int i = lane; i < 2048; i += 64) a = fmaf(pp[i], ww[(size_t)i * 256], a);
;                 a = wave_sum(a);
;                 if (lane == 0) ((float*)(ws + WS_SMALL))[kv * 256 + j] = a; }
.LBB0_391:
	s_addk_i32 s4, 0x200
	s_lshl_b32 s5, s27, 3
	s_cmp_ge_u32 s4, s5
	s_cselect_b32 s5, s5, 0
	s_sub_u32 s4, s4, s5
	s_cmpk_gt_i32 s4, 0x1ff
	s_cbranch_scc1 .LBB0_397
	s_mov_b32 s18, 8
	s_ashr_i32 s19, s18, 31
	s_ashr_i32 s16, s4, 8
	s_and_b32 s5, s4, 0xff
	s_lshl_b64 s[18:19], s[18:19], 3
	s_add_u32 s18, s0, s18
	s_addc_u32 s19, s1, s19
	s_lshl_b32 s22, s16, 11
	s_ashr_i32 s17, s16, 31
	s_lshl_b64 s[20:21], s[10:11], 14
	s_ashr_i32 s23, s22, 31
	s_lshl_b64 s[16:17], s[16:17], 21
	s_add_u32 s11, s14, s16
	s_addc_u32 s14, s15, s17
	s_lshl_b32 s5, s5, 2
	s_add_u32 s5, s6, s5
	s_addc_u32 s7, s7, 0
	s_add_u32 s6, s5, s11
	s_load_dwordx2 s[18:19], s[18:19], 0x0
	v_lshlrev_b32_e32 v80, 10, v33
	s_addc_u32 s7, s7, s14
	s_waitcnt vmcnt(1)
	v_lshl_add_u64 v[0:1], s[6:7], 0, v[80:81]
	s_mov_b64 s[6:7], 0x70000
	v_lshl_add_u64 v[0:1], v[0:1], 0, s[6:7]
	s_lshl_b64 s[6:7], s[22:23], 2
	s_add_u32 s5, s20, s6
	s_addc_u32 s7, s21, s7
	s_waitcnt lgkmcnt(0)
	s_add_u32 s6, s18, s5
	v_lshlrev_b32_e32 v80, 2, v33
	s_addc_u32 s7, s19, s7
	v_lshl_add_u64 v[2:3], s[6:7], 0, v[80:81]
	s_mov_b64 s[6:7], 0x700
	v_or_b32_e32 v4, 0xfffffe00, v33
	v_lshl_add_u64 v[2:3], v[2:3], 0, s[6:7]
	v_mov_b32_e32 v5, 0
	s_mov_b64 s[6:7], 0

;     __host__ __device__ bool next(int i, Unit& u) const {
;         const long L = (long)i * G + c; if (L >= nwg) return false;
;         int wgid = (int)L; { const int q = nwg / NXCD, r = nwg % NXCD, xcd = wgid % NXCD, off = wgid / NXCD; wgid = (xcd < r ? xcd * (q + 1) : r * (q + 1) + (xcd - r) * q) + off; }
;         const int nig = WGM * nN, gid = wgid / nig, fm = gid * WGM, gsz = (nM - fm) < WGM ? (nM - fm) : WGM;
;         u.pm = fm + ((wgid % nig) % gsz); u.pn = (wgid % nig) / gsz; return true;
;     }
; template <class Epi, class Sched, bool ALIGN_EPI = false, bool SP2 = false>
; __device__ __forceinline__ void gemm_phase(PG8_LAS unsigned char* lds, const Gemm g, const Sched& S, const Epi& E, int tid_in) {
;     ...
;     Unit cur, nxt; int ui = 0;
;     if (!S.next(0, cur)) return;
.LBB0_423:
	s_nop 0
	s_nop 0
	s_nop 0
	s_nop 0
	s_nop 0
	s_nop 0
	s_nop 0
	s_nop 0
	s_nop 0
	s_nop 0
	s_nop 0
	s_or_b64 exec, exec, s[4:5]
	s_mov_b32 s10, s20
	s_mov_b64 s[4:5], s[58:59]
	s_mov_b32 s52, s69
	s_mov_b32 s53, s2
	s_barrier
	v_mov_b32_e32 v8, v146
	s_cmpk_lt_i32 s53, 0xc00
	s_cselect_b64 s[6:7], -1, 0
	s_cmpk_gt_i32 s53, 0xbff
	v_readfirstlane_b32 s20, v8
	s_cbranch_scc1 .LBB0_425
	s_ashr_i32 s8, s53, 31
	s_lshr_b32 s8, s8, 29
	s_add_i32 s8, s53, s8
	s_ashr_i32 s9, s8, 3
	s_and_b32 s8, s8, -8
	s_sub_i32 s8, s53, s8
	s_cmp_lt_i32 s8, 0
	s_movk_i32 s11, 0x181
	s_cselect_b32 s11, s11, 0x180
	s_mul_i32 s8, s8, s11
	s_add_i32 s8, s8, s9
	s_mul_hi_i32 s9, s8, 0x2aaaaaab
	s_lshr_b32 s11, s9, 31
	s_ashr_i32 s9, s9, 5
	s_add_i32 s9, s9, s11
	s_lshl_b32 s11, s9, 3
	s_mulk_i32 s9, 0xc0
	s_sub_i32 s8, s8, s9
	s_bfe_u32 s9, s8, 0x3001c
	s_add_i32 s9, s8, s9
	s_sext_i32_i16 s12, s9
	s_and_b32 s9, s9, 0xfff8
	s_sub_i32 s8, s8, s9
	s_sext_i32_i16 s8, s8
	s_add_i32 s38, s11, s8
	s_ashr_i32 s36, s12, 3

; __device__ __forceinline__ float bflo(unsigned w) { return __uint_as_float(w << 16); }
; __device__ __forceinline__ float bfhi(unsigned w) { return __uint_as_float(w & 0xffff0000u); }
; __device__ __forceinline__ void moba_unit(LAS unsigned char* lds, const unsigned char* hb, const float* kmean, bf16_t* omix, int b, int hd, int blk, int tid) {
;     ...
;         { const int qi = tid & 255, part = tid >> 8; float q[64];
;             const u32x4* qp = (const u32x4*)(Qb + (size_t)qi * 64);
; #pragma unroll
;             for (int c = 0; c < 8; ++c) { const u32x4 v = qp[c]; q[8 * c] = bflo(v.x); q[8 * c + 1] = bfhi(v.x); q[8 * c + 2] = bflo(v.y); q[8 * c + 3] = bfhi(v.y); q[8 * c + 4] = bflo(v.z); q[8 * c + 5] = bfhi(v.z); q[8 * c + 6] = bflo(v.w); q[8 * c + 7] = bfhi(v.w); }
;             for (int n = part; n < blk; n += 2) { float a = 0.f;
; #pragma unroll
;                 for (int d = 0; d < 64; ++d) a = fmaf(q[d], km[n * 64 + d], a);
;                 sc[qi * 33 + n] = a; } }
.LBB0_856:
	ds_read_b128 v[68:71], v66
	ds_read_b128 v[72:75], v66 offset:16
	ds_read_b128 v[76:79], v66 offset:32
	ds_read_b128 v[82:85], v66 offset:48
	ds_read_b128 v[214:217], v66 offset:64
	ds_read_b128 v[218:221], v66 offset:80
	ds_read_b128 v[222:225], v66 offset:96
	ds_read_b128 v[226:229], v66 offset:112
	ds_read_b128 v[230:233], v66 offset:128
	ds_read_b128 v[236:239], v66 offset:144
	ds_read_b128 v[240:243], v66 offset:160
	ds_read_b128 v[244:247], v66 offset:176
	v_add_u32_e32 v0, 2, v0
	v_cmp_le_i32_e32 vcc, s5, v0
	s_or_b64 s[8:9], vcc, s[8:9]
	s_waitcnt lgkmcnt(11)
	v_fma_f32 v67, v1, v68, 0
	v_fmac_f32_e32 v67, v2, v69
	v_fmac_f32_e32 v67, v3, v70
	v_fmac_f32_e32 v67, v4, v71
	s_waitcnt lgkmcnt(10)
	v_fmac_f32_e32 v67, v5, v72
	v_fmac_f32_e32 v67, v6, v73
	v_fmac_f32_e32 v67, v7, v74
	v_fmac_f32_e32 v67, v8, v75
	s_waitcnt lgkmcnt(9)
	v_fmac_f32_e32 v67, v9, v76
	v_fmac_f32_e32 v67, v10, v77
	v_fmac_f32_e32 v67, v11, v78
	v_fmac_f32_e32 v67, v12, v79
	s_waitcnt lgkmcnt(8)
	v_fmac_f32_e32 v67, v13, v82
	v_fmac_f32_e32 v67, v14, v83
	v_fmac_f32_e32 v67, v15, v84
	v_fmac_f32_e32 v67, v16, v85
	ds_read_b128 v[68:71], v66 offset:192
	ds_read_b128 v[72:75], v66 offset:208
	ds_read_b128 v[76:79], v66 offset:224
	ds_read_b128 v[82:85], v66 offset:240
	v_add_u32_e32 v66, 0x200, v66
	s_waitcnt lgkmcnt(11)
	v_fmac_f32_e32 v67, v17, v214
	v_fmac_f32_e32 v67, v18, v215
	v_fmac_f32_e32 v67, v19, v216
	v_fmac_f32_e32 v67, v20, v217
	s_waitcnt lgkmcnt(10)
	v_fmac_f32_e32 v67, v21, v218
	v_fmac_f32_e32 v67, v22, v219
	v_fmac_f32_e32 v67, v23, v220
	v_fmac_f32_e32 v67, v24, v221
	s_waitcnt lgkmcnt(9)
	v_fmac_f32_e32 v67, v25, v222
	v_fmac_f32_e32 v67, v26, v223
	v_fmac_f32_e32 v67, v27, v224
	v_fmac_f32_e32 v67, v28, v225
	s_waitcnt lgkmcnt(8)
	v_fmac_f32_e32 v67, v29, v226
	v_fmac_f32_e32 v67, v30, v227
	v_fmac_f32_e32 v67, v31, v228
	v_fmac_f32_e32 v67, v32, v229
	s_waitcnt lgkmcnt(7)
	v_fmac_f32_e32 v67, v33, v230
	v_fmac_f32_e32 v67, v34, v231
	v_fmac_f32_e32 v67, v35, v232
	v_fmac_f32_e32 v67, v36, v233
	s_waitcnt lgkmcnt(6)
	v_fmac_f32_e32 v67, v37, v236
	v_fmac_f32_e32 v67, v38, v237
	v_fmac_f32_e32 v67, v39, v238
	v_fmac_f32_e32 v67, v40, v239
	s_waitcnt lgkmcnt(5)
	v_fmac_f32_e32 v67, v41, v240
	v_fmac_f32_e32 v67, v42, v241
	v_fmac_f32_e32 v67, v43, v242
	v_fmac_f32_e32 v67, v44, v243
	s_waitcnt lgkmcnt(4)
	v_fmac_f32_e32 v67, v45, v244
	v_fmac_f32_e32 v67, v46, v245
	v_fmac_f32_e32 v67, v47, v246
	v_fmac_f32_e32 v67, v48, v247
	s_waitcnt lgkmcnt(3)
	v_fmac_f32_e32 v67, v49, v68
	v_fmac_f32_e32 v67, v50, v69
	v_fmac_f32_e32 v67, v51, v70
	v_fmac_f32_e32 v67, v52, v71
	s_waitcnt lgkmcnt(2)
	v_fmac_f32_e32 v67, v53, v72
	v_fmac_f32_e32 v67, v54, v73
	v_fmac_f32_e32 v67, v55, v74
	v_fmac_f32_e32 v67, v56, v75
	s_waitcnt lgkmcnt(1)
	v_fmac_f32_e32 v67, v57, v76
	v_fmac_f32_e32 v67, v58, v77
	v_fmac_f32_e32 v67, v59, v78
	v_fmac_f32_e32 v67, v60, v79
	s_waitcnt lgkmcnt(0)
	v_fmac_f32_e32 v67, v61, v82
	v_fmac_f32_e32 v67, v62, v83
	v_fmac_f32_e32 v67, v63, v84
	v_fmac_f32_e32 v67, v64, v85
	ds_write_b32 v65, v67
	v_add_u32_e32 v65, 8, v65
	s_andn2_b64 exec, exec, s[8:9]
	s_cbranch_execnz .LBB0_856
